# convert_weights: tile and gain loads of all 4 jobs in flight together, gains applied after one drain (was 8 serialized round trips)
# speedup vs baseline: 1.0103x; 1.0103x over previous
.LBB0_1390:
	v_mov_b32_e32 v100, 1.0
	v_mov_b32_e32 v102, 1.0
	v_mov_b32_e32 v104, 1.0
	v_mov_b32_e32 v106, 1.0
	v_mov_b32_e32 v108, 1.0
	v_mov_b32_e32 v110, 1.0
	v_mov_b32_e32 v112, 1.0
	v_mov_b32_e32 v114, 1.0
	s_cmpk_gt_i32 s53, 0x5bf
	s_mov_b64 s[40:41], -1
	s_cbranch_scc0 .LBB0_1406
	s_cmpk_gt_u32 s53, 0x6bf
	s_cbranch_scc0 .LBB0_1403
	s_cmpk_gt_u32 s53, 0x73f
	s_mov_b64 s[8:9], -1
	s_cbranch_scc0 .LBB0_1401
	s_cmpk_gt_u32 s53, 0x83f
	s_cbranch_scc0 .LBB0_1398
	s_cmpk_gt_u32 s53, 0xc3f
	s_mov_b64 s[2:3], -1
	s_cbranch_scc0 .LBB0_1396
	s_and_b32 s26, s93, 0x7fffffc0
	s_and_b32 s0, s52, 0x3c0
	s_mov_b64 s[2:3], 0

.LBB0_1408:
	s_ashr_i32 s1, s0, 31
	s_lshl_b64 s[40:41], s[0:1], 2
	v_add_u32_e32 v32, s26, v1
	s_add_u32 s38, s38, s40
	s_addc_u32 s39, s39, s41
	v_ashrrev_i32_e32 v33, 31, v32
	v_lshl_add_u64 v[34:35], s[38:39], 0, v[2:3]
	v_mul_lo_u32 v30, s10, v33
	v_mul_lo_u32 v31, s11, v32
	v_mad_u64_u32 v[28:29], s[38:39], s10, v32, 0
	v_add3_u32 v29, v29, v30, v31
	v_lshl_add_u64 v[28:29], v[28:29], 2, v[34:35]
	global_load_dwordx4 v[28:31], v[28:29], off
	s_cmp_lg_u64 s[30:31], 0
	s_cselect_b64 s[38:39], -1, 0
	s_cmp_eq_u64 s[30:31], 0
	v_lshl_add_u64 v[36:37], v[32:33], 2, s[30:31]
	s_cbranch_scc1 .LBB0_1410
	global_load_dword v100, v[36:37], off
.LBB0_1410:
	v_add_u32_e32 v32, 32, v32
	v_ashrrev_i32_e32 v33, 31, v32
	v_mul_lo_u32 v43, s10, v33
	v_mul_lo_u32 v44, s11, v32
	v_mad_u64_u32 v[32:33], s[10:11], s10, v32, 0
	v_add3_u32 v33, v33, v43, v44
	v_lshl_add_u64 v[32:33], v[32:33], 2, v[34:35]
	global_load_dwordx4 v[32:35], v[32:33], off
	s_andn2_b64 vcc, exec, s[38:39]
	s_cbranch_vccnz .LBB0_1412
	global_load_dword v102, v[36:37], off offset:128

.LBB0_1432:
	s_ashr_i32 s81, s80, 31
	s_lshl_b64 s[42:43], s[80:81], 2
	v_add_u32_e32 v24, s76, v1
	s_add_u32 s40, s40, s42
	s_addc_u32 s41, s41, s43
	v_ashrrev_i32_e32 v25, 31, v24
	v_lshl_add_u64 v[26:27], s[40:41], 0, v[2:3]
	v_mul_lo_u32 v14, s10, v25
	v_mul_lo_u32 v15, s11, v24
	v_mad_u64_u32 v[12:13], s[40:41], s10, v24, 0
	v_add3_u32 v13, v13, v14, v15
	v_lshl_add_u64 v[12:13], v[12:13], 2, v[26:27]
	global_load_dwordx4 v[12:15], v[12:13], off
	s_cmp_lg_u64 s[30:31], 0
	s_cselect_b64 s[40:41], -1, 0
	s_cmp_eq_u64 s[30:31], 0
	v_lshl_add_u64 v[36:37], v[24:25], 2, s[30:31]
	s_cbranch_scc1 .LBB0_1434
	global_load_dword v104, v[36:37], off
.LBB0_1434:
	v_add_u32_e32 v24, 32, v24
	v_ashrrev_i32_e32 v25, 31, v24
	v_mul_lo_u32 v43, s10, v25
	v_mul_lo_u32 v44, s11, v24
	v_mad_u64_u32 v[24:25], s[10:11], s10, v24, 0
	v_add3_u32 v25, v25, v43, v44
	v_lshl_add_u64 v[24:25], v[24:25], 2, v[26:27]
	global_load_dwordx4 v[24:27], v[24:25], off
	s_andn2_b64 vcc, exec, s[40:41]
	s_cbranch_vccnz .LBB0_1436
	global_load_dword v106, v[36:37], off offset:128

.LBB0_1456:
	s_ashr_i32 s75, s74, 31
	s_lshl_b64 s[50:51], s[74:75], 2
	v_add_u32_e32 v16, s72, v1
	s_add_u32 s42, s42, s50
	s_addc_u32 s43, s43, s51
	v_ashrrev_i32_e32 v17, 31, v16
	v_lshl_add_u64 v[18:19], s[42:43], 0, v[2:3]
	v_mul_lo_u32 v6, s30, v17
	v_mul_lo_u32 v7, s31, v16
	v_mad_u64_u32 v[4:5], s[42:43], s30, v16, 0
	v_add3_u32 v5, v5, v6, v7
	v_lshl_add_u64 v[4:5], v[4:5], 2, v[18:19]
	global_load_dwordx4 v[4:7], v[4:5], off
	s_cmp_lg_u64 s[40:41], 0
	s_cselect_b64 s[42:43], -1, 0
	s_cmp_eq_u64 s[40:41], 0
	v_lshl_add_u64 v[36:37], v[16:17], 2, s[40:41]
	s_cbranch_scc1 .LBB0_1458
	global_load_dword v108, v[36:37], off
.LBB0_1458:
	v_add_u32_e32 v16, 32, v16
	v_ashrrev_i32_e32 v17, 31, v16
	v_mul_lo_u32 v43, s30, v17
	v_mul_lo_u32 v44, s31, v16
	v_mad_u64_u32 v[16:17], s[30:31], s30, v16, 0
	v_add3_u32 v17, v17, v43, v44
	v_lshl_add_u64 v[16:17], v[16:17], 2, v[18:19]
	global_load_dwordx4 v[16:19], v[16:17], off
	s_andn2_b64 vcc, exec, s[42:43]
	s_cbranch_vccnz .LBB0_1460
	global_load_dword v110, v[36:37], off offset:128

.LBB0_1480:
	s_ashr_i32 s83, s82, 31
	s_lshl_b64 vcc, s[82:83], 2
	v_add_u32_e32 v20, s78, v1
	s_add_u32 s50, s50, vcc_lo
	s_addc_u32 s51, s51, vcc_hi
	v_ashrrev_i32_e32 v21, 31, v20
	v_lshl_add_u64 v[22:23], s[50:51], 0, v[2:3]
	v_mul_lo_u32 v10, s40, v21
	v_mul_lo_u32 v11, s41, v20
	v_mad_u64_u32 v[8:9], s[50:51], s40, v20, 0
	v_add3_u32 v9, v9, v10, v11
	v_lshl_add_u64 v[8:9], v[8:9], 2, v[22:23]
	global_load_dwordx4 v[8:11], v[8:9], off
	s_cmp_lg_u64 s[42:43], 0
	s_cselect_b64 s[50:51], -1, 0
	s_cmp_eq_u64 s[42:43], 0
	v_lshl_add_u64 v[36:37], v[20:21], 2, s[42:43]
	s_cbranch_scc1 .LBB0_1482
	global_load_dword v112, v[36:37], off
.LBB0_1482:
	v_add_u32_e32 v20, 32, v20
	v_ashrrev_i32_e32 v21, 31, v20
	v_mul_lo_u32 v43, s40, v21
	v_mul_lo_u32 v44, s41, v20
	v_mad_u64_u32 v[20:21], s[40:41], s40, v20, 0
	v_add3_u32 v21, v21, v43, v44
	v_lshl_add_u64 v[20:21], v[20:21], 2, v[22:23]
	global_load_dwordx4 v[20:23], v[20:21], off
	s_andn2_b64 vcc, exec, s[50:51]
	s_cbranch_vccnz .LBB0_1484
	global_load_dword v114, v[36:37], off offset:128
.LBB0_1484:
	s_waitcnt vmcnt(0)
	v_pk_mul_f32 v[30:31], v[30:31], v[100:101] op_sel_hi:[1,0]
	v_pk_mul_f32 v[28:29], v[28:29], v[100:101] op_sel_hi:[1,0]
	v_pk_mul_f32 v[34:35], v[34:35], v[102:103] op_sel_hi:[1,0]
	v_pk_mul_f32 v[32:33], v[32:33], v[102:103] op_sel_hi:[1,0]
	v_pk_mul_f32 v[14:15], v[14:15], v[104:105] op_sel_hi:[1,0]
	v_pk_mul_f32 v[12:13], v[12:13], v[104:105] op_sel_hi:[1,0]
	v_pk_mul_f32 v[26:27], v[26:27], v[106:107] op_sel_hi:[1,0]
	v_pk_mul_f32 v[24:25], v[24:25], v[106:107] op_sel_hi:[1,0]
	v_pk_mul_f32 v[6:7], v[6:7], v[108:109] op_sel_hi:[1,0]
	v_pk_mul_f32 v[4:5], v[4:5], v[108:109] op_sel_hi:[1,0]
	v_pk_mul_f32 v[18:19], v[18:19], v[110:111] op_sel_hi:[1,0]
	v_pk_mul_f32 v[16:17], v[16:17], v[110:111] op_sel_hi:[1,0]
	v_pk_mul_f32 v[10:11], v[10:11], v[112:113] op_sel_hi:[1,0]
	v_pk_mul_f32 v[8:9], v[8:9], v[112:113] op_sel_hi:[1,0]
	v_pk_mul_f32 v[22:23], v[22:23], v[114:115] op_sel_hi:[1,0]
	v_pk_mul_f32 v[20:21], v[20:21], v[114:115] op_sel_hi:[1,0]
	ds_write2_b32 v42, v28, v29 offset1:1
	ds_write2_b32 v42, v30, v31 offset0:2 offset1:3
	v_add_u32_e32 v28, 0x2080, v42
	v_cndmask_b32_e64 v29, 0, 1, s[38:39]
	s_waitcnt vmcnt(0)
	ds_write2_b32 v28, v32, v33 offset1:1
	v_add_u32_e32 v28, 0x2088, v42
	v_cmp_ne_u32_e64 s[42:43], 1, v29
	s_andn2_b64 vcc, exec, s[38:39]
	ds_write2_b32 v28, v34, v35 offset1:1
	s_cbranch_vccnz .LBB0_1503
	v_add_u32_e32 v28, 0x4100, v42
	ds_write2_b32 v28, v12, v13 offset1:1
	v_add_u32_e32 v28, 0x4108, v42
	ds_write2_b32 v28, v14, v15 offset1:1
	v_add_u32_e32 v28, 0x6180, v42
	ds_write2_b32 v28, v24, v25 offset1:1
	v_add_u32_e32 v28, 0x6188, v42
	ds_write2_b32 v28, v26, v27 offset1:1
	v_cndmask_b32_e64 v28, 0, 1, s[10:11]
	v_cmp_ne_u32_e64 s[40:41], 1, v28
	s_andn2_b64 vcc, exec, s[10:11]
	s_cbranch_vccz .LBB0_1504
